# GEMM phases: static s_setprio 3 (instead of 1) for waves 0-3, toggles removed
# speedup vs baseline: 1.0064x; 1.0019x over previous
.Lsp_gemm:
	v_readfirstlane_b32 s100, v206
	s_nop 3
	s_cmp_ge_u32 s100, 0x100
	s_cbranch_scc1 .Lsp_done
	s_setprio 3
